# v27 plus grid-barrier XCD leaders released on the cross-XCD arrival count instead of waiting for the last leader to bump the top generation word
# speedup vs baseline: 1.0039x; 1.0023x over previous
.LBB0_214:
	s_or_b64 exec, exec, s[6:7]
	v_cvt_f32_u32_e32 v3, v0
	s_waitcnt vmcnt(0)
	v_readfirstlane_b32 s4, v2
	s_add_u32 s6, s86, 0x7500
	s_addc_u32 s7, s87, 0
	v_rcp_iflag_f32_e32 v3, v3
	v_add_u32_e32 v1, s4, v1
	v_add_u32_e32 v4, 1, v1
	s_mov_b64 s[8:9], -1
	v_mul_f32_e32 v2, 0x4f7ffffe, v3
	v_cvt_u32_f32_e32 v2, v2
	v_sub_u32_e32 v3, 0, v0
	v_mul_lo_u32 v3, v3, v2
	v_mul_hi_u32 v3, v2, v3
	v_add_u32_e32 v2, v2, v3
	v_mul_hi_u32 v2, v1, v2
	v_mul_lo_u32 v3, v2, v0
	v_sub_u32_e32 v1, v1, v3
	v_add_u32_e32 v5, 1, v2
	v_cmp_ge_u32_e32 vcc, v1, v0
	v_sub_u32_e32 v3, v1, v0
	s_nop 0
	v_cndmask_b32_e32 v2, v2, v5, vcc
	v_cndmask_b32_e32 v1, v1, v3, vcc
	v_add_u32_e32 v3, 1, v2
	v_cmp_ge_u32_e32 vcc, v1, v0
	s_nop 1
	v_cndmask_b32_e32 v2, v2, v3, vcc
	v_mul_lo_u32 v1, v0, v2
	v_add_u32_e32 v0, v1, v0
	v_cmp_ne_u32_e32 vcc, v4, v0
	v_mov_b32_e32 v4, v0
	v_mov_b64_e32 v[0:1], s[6:7]
	s_and_saveexec_b64 s[4:5], vcc
	s_cbranch_execz .LBB0_226
	v_mov_b32_e32 v0, 0
	global_load_dword v1, v0, s[6:7] offset:-256 sc1
	s_mov_b64 s[14:15], 0
	s_waitcnt vmcnt(0)
	v_cmp_lt_u32_e32 vcc, v1, v4
	s_and_saveexec_b64 s[10:11], vcc
	s_cbranch_execz .LBB0_225
	s_add_u32 s8, s86, 0x4200
	s_addc_u32 s9, s87, 0
	s_mov_b32 s26, 1
	s_branch .LBB0_218

.LBB0_220:
	global_load_dword v1, v0, s[6:7] offset:-256 sc1
	s_add_i32 s26, s26, 1
	s_mov_b64 s[18:19], -1
	s_waitcnt vmcnt(0)
	v_cmp_ge_u32_e32 vcc, v1, v4
	s_orn2_b64 s[22:23], vcc, exec
	s_branch .LBB0_217

.LBB0_300:
	s_or_b64 exec, exec, s[6:7]
	v_cvt_f32_u32_e32 v3, v0
	s_waitcnt vmcnt(0)
	v_readfirstlane_b32 s4, v2
	s_add_u32 s6, s86, 0x7500
	s_addc_u32 s7, s87, 0
	v_rcp_iflag_f32_e32 v3, v3
	v_add_u32_e32 v1, s4, v1
	v_add_u32_e32 v4, 1, v1
	s_mov_b64 s[8:9], -1
	v_mul_f32_e32 v2, 0x4f7ffffe, v3
	v_cvt_u32_f32_e32 v2, v2
	v_sub_u32_e32 v3, 0, v0
	v_mul_lo_u32 v3, v3, v2
	v_mul_hi_u32 v3, v2, v3
	v_add_u32_e32 v2, v2, v3
	v_mul_hi_u32 v2, v1, v2
	v_mul_lo_u32 v3, v2, v0
	v_sub_u32_e32 v1, v1, v3
	v_add_u32_e32 v5, 1, v2
	v_cmp_ge_u32_e32 vcc, v1, v0
	v_sub_u32_e32 v3, v1, v0
	s_nop 0
	v_cndmask_b32_e32 v2, v2, v5, vcc
	v_cndmask_b32_e32 v1, v1, v3, vcc
	v_add_u32_e32 v3, 1, v2
	v_cmp_ge_u32_e32 vcc, v1, v0
	s_nop 1
	v_cndmask_b32_e32 v2, v2, v3, vcc
	v_mul_lo_u32 v1, v0, v2
	v_add_u32_e32 v0, v1, v0
	v_cmp_ne_u32_e32 vcc, v4, v0
	v_mov_b32_e32 v4, v0
	v_mov_b64_e32 v[0:1], s[6:7]
	s_and_saveexec_b64 s[4:5], vcc
	s_cbranch_execz .LBB0_312
	v_mov_b32_e32 v0, 0
	global_load_dword v1, v0, s[6:7] offset:-256 sc1
	s_mov_b64 s[12:13], 0
	s_waitcnt vmcnt(0)
	v_cmp_lt_u32_e32 vcc, v1, v4
	s_and_saveexec_b64 s[10:11], vcc
	s_cbranch_execz .LBB0_311
	s_add_u32 s8, s86, 0x4200
	s_addc_u32 s9, s87, 0
	s_mov_b32 s22, 1
	s_branch .LBB0_304

.LBB0_306:
	global_load_dword v1, v0, s[6:7] offset:-256 sc1
	s_add_i32 s22, s22, 1
	s_mov_b64 s[16:17], -1
	s_waitcnt vmcnt(0)
	v_cmp_ge_u32_e32 vcc, v1, v4
	s_orn2_b64 s[20:21], vcc, exec
	s_branch .LBB0_303

.LBB0_628:
	s_or_b64 exec, exec, s[8:9]
	v_cvt_f32_u32_e32 v3, v0
	s_waitcnt vmcnt(0)
	v_readfirstlane_b32 s6, v2
	s_add_u32 s8, s86, 0x7500
	s_addc_u32 s9, s87, 0
	v_rcp_iflag_f32_e32 v3, v3
	v_add_u32_e32 v1, s6, v1
	v_add_u32_e32 v4, 1, v1
	s_mov_b64 s[10:11], -1
	v_mul_f32_e32 v2, 0x4f7ffffe, v3
	v_cvt_u32_f32_e32 v2, v2
	v_sub_u32_e32 v3, 0, v0
	v_mul_lo_u32 v3, v3, v2
	v_mul_hi_u32 v3, v2, v3
	v_add_u32_e32 v2, v2, v3
	v_mul_hi_u32 v2, v1, v2
	v_mul_lo_u32 v3, v2, v0
	v_sub_u32_e32 v1, v1, v3
	v_add_u32_e32 v5, 1, v2
	v_cmp_ge_u32_e32 vcc, v1, v0
	v_sub_u32_e32 v3, v1, v0
	s_nop 0
	v_cndmask_b32_e32 v2, v2, v5, vcc
	v_cndmask_b32_e32 v1, v1, v3, vcc
	v_add_u32_e32 v3, 1, v2
	v_cmp_ge_u32_e32 vcc, v1, v0
	s_nop 1
	v_cndmask_b32_e32 v2, v2, v3, vcc
	v_mul_lo_u32 v1, v0, v2
	v_add_u32_e32 v0, v1, v0
	v_cmp_ne_u32_e32 vcc, v4, v0
	v_mov_b32_e32 v4, v0
	v_mov_b64_e32 v[0:1], s[8:9]
	s_and_saveexec_b64 s[6:7], vcc
	s_cbranch_execz .LBB0_640
	v_mov_b32_e32 v0, 0
	global_load_dword v1, v0, s[8:9] offset:-256 sc1
	s_mov_b64 s[14:15], 0
	s_waitcnt vmcnt(0)
	v_cmp_lt_u32_e32 vcc, v1, v4
	s_and_saveexec_b64 s[12:13], vcc
	s_cbranch_execz .LBB0_639
	s_add_u32 s10, s86, 0x4200
	s_addc_u32 s11, s87, 0
	s_mov_b32 s24, 1
	s_branch .LBB0_632

.LBB0_634:
	global_load_dword v1, v0, s[8:9] offset:-256 sc1
	s_add_i32 s24, s24, 1
	s_mov_b64 s[18:19], -1
	s_waitcnt vmcnt(0)
	v_cmp_ge_u32_e32 vcc, v1, v4
	s_orn2_b64 s[22:23], vcc, exec
	s_branch .LBB0_631

.LBB0_828:
	s_or_b64 exec, exec, s[8:9]
	v_cvt_f32_u32_e32 v3, v0
	s_waitcnt vmcnt(0)
	v_readfirstlane_b32 s6, v2
	s_add_u32 s8, s86, 0x7500
	s_addc_u32 s9, s87, 0
	v_rcp_iflag_f32_e32 v3, v3
	v_add_u32_e32 v1, s6, v1
	v_add_u32_e32 v4, 1, v1
	s_mov_b64 s[12:13], -1
	v_mul_f32_e32 v2, 0x4f7ffffe, v3
	v_cvt_u32_f32_e32 v2, v2
	v_sub_u32_e32 v3, 0, v0
	v_mul_lo_u32 v3, v3, v2
	v_mul_hi_u32 v3, v2, v3
	v_add_u32_e32 v2, v2, v3
	v_mul_hi_u32 v2, v1, v2
	v_mul_lo_u32 v3, v2, v0
	v_sub_u32_e32 v1, v1, v3
	v_add_u32_e32 v5, 1, v2
	v_cmp_ge_u32_e32 vcc, v1, v0
	v_sub_u32_e32 v3, v1, v0
	s_nop 0
	v_cndmask_b32_e32 v2, v2, v5, vcc
	v_cndmask_b32_e32 v1, v1, v3, vcc
	v_add_u32_e32 v3, 1, v2
	v_cmp_ge_u32_e32 vcc, v1, v0
	s_nop 1
	v_cndmask_b32_e32 v2, v2, v3, vcc
	v_mul_lo_u32 v1, v0, v2
	v_add_u32_e32 v0, v1, v0
	v_cmp_ne_u32_e32 vcc, v4, v0
	v_mov_b32_e32 v4, v0
	v_mov_b64_e32 v[0:1], s[8:9]
	s_and_saveexec_b64 s[6:7], vcc
	s_cbranch_execz .LBB0_840
	v_mov_b32_e32 v0, 0
	global_load_dword v1, v0, s[8:9] offset:-256 sc1
	s_mov_b64 s[16:17], 0
	s_waitcnt vmcnt(0)
	v_cmp_lt_u32_e32 vcc, v1, v4
	s_and_saveexec_b64 s[14:15], vcc
	s_cbranch_execz .LBB0_839
	s_add_u32 s12, s86, 0x4200
	s_addc_u32 s13, s87, 0
	s_mov_b32 s28, 1
	s_branch .LBB0_832

.LBB0_834:
	global_load_dword v1, v0, s[8:9] offset:-256 sc1
	s_add_i32 s28, s28, 1
	s_mov_b64 s[20:21], -1
	s_waitcnt vmcnt(0)
	v_cmp_ge_u32_e32 vcc, v1, v4
	s_orn2_b64 s[26:27], vcc, exec
	s_branch .LBB0_831

.LBB0_1042:
	s_or_b64 exec, exec, s[8:9]
	v_cvt_f32_u32_e32 v3, v0
	s_waitcnt vmcnt(0)
	v_readfirstlane_b32 s6, v2
	s_add_u32 s8, s70, 0x7500
	s_addc_u32 s9, s71, 0
	v_rcp_iflag_f32_e32 v3, v3
	v_add_u32_e32 v1, s6, v1
	v_add_u32_e32 v4, 1, v1
	s_mov_b64 s[10:11], -1
	v_mul_f32_e32 v2, 0x4f7ffffe, v3
	v_cvt_u32_f32_e32 v2, v2
	v_sub_u32_e32 v3, 0, v0
	v_mul_lo_u32 v3, v3, v2
	v_mul_hi_u32 v3, v2, v3
	v_add_u32_e32 v2, v2, v3
	v_mul_hi_u32 v2, v1, v2
	v_mul_lo_u32 v3, v2, v0
	v_sub_u32_e32 v1, v1, v3
	v_add_u32_e32 v5, 1, v2
	v_cmp_ge_u32_e32 vcc, v1, v0
	v_sub_u32_e32 v3, v1, v0
	s_nop 0
	v_cndmask_b32_e32 v2, v2, v5, vcc
	v_cndmask_b32_e32 v1, v1, v3, vcc
	v_add_u32_e32 v3, 1, v2
	v_cmp_ge_u32_e32 vcc, v1, v0
	s_nop 1
	v_cndmask_b32_e32 v2, v2, v3, vcc
	v_mul_lo_u32 v1, v0, v2
	v_add_u32_e32 v0, v1, v0
	v_cmp_ne_u32_e32 vcc, v4, v0
	v_mov_b32_e32 v4, v0
	v_mov_b64_e32 v[0:1], s[8:9]
	s_and_saveexec_b64 s[6:7], vcc
	s_cbranch_execz .LBB0_1054
	v_mov_b32_e32 v0, 0
	global_load_dword v1, v0, s[8:9] offset:-256 sc1
	s_mov_b64 s[14:15], 0
	s_waitcnt vmcnt(0)
	v_cmp_lt_u32_e32 vcc, v1, v4
	s_and_saveexec_b64 s[12:13], vcc
	s_cbranch_execz .LBB0_1053
	s_add_u32 s10, s70, 0x4200
	s_addc_u32 s11, s71, 0
	s_mov_b32 s24, 1
	s_branch .LBB0_1046

.LBB0_1549:
	s_or_b64 exec, exec, s[10:11]
	v_cvt_f32_u32_e32 v3, v0
	s_waitcnt vmcnt(0)
	v_readfirstlane_b32 s8, v2
	s_add_u32 s10, s70, 0x7500
	s_addc_u32 s11, s71, 0
	v_rcp_iflag_f32_e32 v3, v3
	v_add_u32_e32 v1, s8, v1
	v_add_u32_e32 v4, 1, v1
	s_mov_b64 s[12:13], -1
	v_mul_f32_e32 v2, 0x4f7ffffe, v3
	v_cvt_u32_f32_e32 v2, v2
	v_sub_u32_e32 v3, 0, v0
	v_mul_lo_u32 v3, v3, v2
	v_mul_hi_u32 v3, v2, v3
	v_add_u32_e32 v2, v2, v3
	v_mul_hi_u32 v2, v1, v2
	v_mul_lo_u32 v3, v2, v0
	v_sub_u32_e32 v1, v1, v3
	v_add_u32_e32 v5, 1, v2
	v_cmp_ge_u32_e32 vcc, v1, v0
	v_sub_u32_e32 v3, v1, v0
	s_nop 0
	v_cndmask_b32_e32 v2, v2, v5, vcc
	v_cndmask_b32_e32 v1, v1, v3, vcc
	v_add_u32_e32 v3, 1, v2
	v_cmp_ge_u32_e32 vcc, v1, v0
	s_nop 1
	v_cndmask_b32_e32 v2, v2, v3, vcc
	v_mul_lo_u32 v1, v0, v2
	v_add_u32_e32 v0, v1, v0
	v_cmp_ne_u32_e32 vcc, v4, v0
	v_mov_b32_e32 v4, v0
	v_mov_b64_e32 v[0:1], s[10:11]
	s_and_saveexec_b64 s[8:9], vcc
	s_cbranch_execz .LBB0_1561
	v_mov_b32_e32 v0, 0
	global_load_dword v1, v0, s[10:11] offset:-256 sc1
	s_mov_b64 s[16:17], 0
	s_waitcnt vmcnt(0)
	v_cmp_lt_u32_e32 vcc, v1, v4
	s_and_saveexec_b64 s[14:15], vcc
	s_cbranch_execz .LBB0_1560
	s_add_u32 s12, s70, 0x4200
	s_addc_u32 s13, s71, 0
	s_mov_b32 s26, 1
	s_branch .LBB0_1553

.LBB0_1555:
	global_load_dword v1, v0, s[10:11] offset:-256 sc1
	s_add_i32 s26, s26, 1
	s_mov_b64 s[20:21], -1
	s_waitcnt vmcnt(0)
	v_cmp_ge_u32_e32 vcc, v1, v4
	s_orn2_b64 s[24:25], vcc, exec
	s_branch .LBB0_1552

.LBB0_1676:
	s_or_b64 exec, exec, s[8:9]
	v_cvt_f32_u32_e32 v3, v0
	s_waitcnt vmcnt(0)
	v_readfirstlane_b32 s6, v2
	s_add_u32 s8, s70, 0x7500
	s_addc_u32 s9, s71, 0
	v_rcp_iflag_f32_e32 v3, v3
	v_add_u32_e32 v1, s6, v1
	v_add_u32_e32 v4, 1, v1
	s_mov_b64 s[12:13], -1
	v_mul_f32_e32 v2, 0x4f7ffffe, v3
	v_cvt_u32_f32_e32 v2, v2
	v_sub_u32_e32 v3, 0, v0
	v_mul_lo_u32 v3, v3, v2
	v_mul_hi_u32 v3, v2, v3
	v_add_u32_e32 v2, v2, v3
	v_mul_hi_u32 v2, v1, v2
	v_mul_lo_u32 v3, v2, v0
	v_sub_u32_e32 v1, v1, v3
	v_add_u32_e32 v5, 1, v2
	v_cmp_ge_u32_e32 vcc, v1, v0
	v_sub_u32_e32 v3, v1, v0
	s_nop 0
	v_cndmask_b32_e32 v2, v2, v5, vcc
	v_cndmask_b32_e32 v1, v1, v3, vcc
	v_add_u32_e32 v3, 1, v2
	v_cmp_ge_u32_e32 vcc, v1, v0
	s_nop 1
	v_cndmask_b32_e32 v2, v2, v3, vcc
	v_mul_lo_u32 v1, v0, v2
	v_add_u32_e32 v0, v1, v0
	v_cmp_ne_u32_e32 vcc, v4, v0
	v_mov_b32_e32 v4, v0
	v_mov_b64_e32 v[0:1], s[8:9]
	s_and_saveexec_b64 s[6:7], vcc
	s_cbranch_execz .LBB0_1688
	v_mov_b32_e32 v0, 0
	global_load_dword v1, v0, s[8:9] offset:-256 sc1
	s_mov_b64 s[18:19], 0
	s_waitcnt vmcnt(0)
	v_cmp_lt_u32_e32 vcc, v1, v4
	s_and_saveexec_b64 s[14:15], vcc
	s_cbranch_execz .LBB0_1687
	s_add_u32 s12, s70, 0x4200
	s_addc_u32 s13, s71, 0
	s_mov_b32 s28, 1
	s_branch .LBB0_1680

.LBB0_1682:
	global_load_dword v1, v0, s[8:9] offset:-256 sc1
	s_add_i32 s28, s28, 1
	s_mov_b64 s[22:23], -1
	s_waitcnt vmcnt(0)
	v_cmp_ge_u32_e32 vcc, v1, v4
	s_orn2_b64 s[26:27], vcc, exec
	s_branch .LBB0_1679

.LBB0_1815:
	s_or_b64 exec, exec, s[10:11]
	v_cvt_f32_u32_e32 v3, v0
	s_waitcnt vmcnt(0)
	v_readfirstlane_b32 s8, v2
	s_add_u32 s10, s70, 0x7500
	s_addc_u32 s11, s71, 0
	v_rcp_iflag_f32_e32 v3, v3
	v_add_u32_e32 v1, s8, v1
	v_add_u32_e32 v4, 1, v1
	s_mov_b64 s[12:13], -1
	v_mul_f32_e32 v2, 0x4f7ffffe, v3
	v_cvt_u32_f32_e32 v2, v2
	v_sub_u32_e32 v3, 0, v0
	v_mul_lo_u32 v3, v3, v2
	v_mul_hi_u32 v3, v2, v3
	v_add_u32_e32 v2, v2, v3
	v_mul_hi_u32 v2, v1, v2
	v_mul_lo_u32 v3, v2, v0
	v_sub_u32_e32 v1, v1, v3
	v_add_u32_e32 v5, 1, v2
	v_cmp_ge_u32_e32 vcc, v1, v0
	v_sub_u32_e32 v3, v1, v0
	s_nop 0
	v_cndmask_b32_e32 v2, v2, v5, vcc
	v_cndmask_b32_e32 v1, v1, v3, vcc
	v_add_u32_e32 v3, 1, v2
	v_cmp_ge_u32_e32 vcc, v1, v0
	s_nop 1
	v_cndmask_b32_e32 v2, v2, v3, vcc
	v_mul_lo_u32 v1, v0, v2
	v_add_u32_e32 v0, v1, v0
	v_cmp_ne_u32_e32 vcc, v4, v0
	v_mov_b32_e32 v4, v0
	v_mov_b64_e32 v[0:1], s[10:11]
	s_and_saveexec_b64 s[8:9], vcc
	s_cbranch_execz .LBB0_1827
	v_mov_b32_e32 v0, 0
	global_load_dword v1, v0, s[10:11] offset:-256 sc1
	s_mov_b64 s[18:19], 0
	s_waitcnt vmcnt(0)
	v_cmp_lt_u32_e32 vcc, v1, v4
	s_and_saveexec_b64 s[14:15], vcc
	s_cbranch_execz .LBB0_1826
	s_add_u32 s12, s70, 0x4200
	s_addc_u32 s13, s71, 0
	s_mov_b32 s28, 1
	s_branch .LBB0_1819

.LBB0_1821:
	global_load_dword v1, v0, s[10:11] offset:-256 sc1
	s_add_i32 s28, s28, 1
	s_mov_b64 s[22:23], -1
	s_waitcnt vmcnt(0)
	v_cmp_ge_u32_e32 vcc, v1, v4
	s_orn2_b64 s[26:27], vcc, exec
	s_branch .LBB0_1818

.LBB0_1942:
	s_or_b64 exec, exec, s[10:11]
	v_cvt_f32_u32_e32 v3, v0
	s_waitcnt vmcnt(0)
	v_readfirstlane_b32 s8, v2
	s_add_u32 s10, s70, 0x7500
	s_addc_u32 s11, s71, 0
	v_rcp_iflag_f32_e32 v3, v3
	v_add_u32_e32 v1, s8, v1
	v_add_u32_e32 v4, 1, v1
	s_mov_b64 s[14:15], -1
	v_mul_f32_e32 v2, 0x4f7ffffe, v3
	v_cvt_u32_f32_e32 v2, v2
	v_sub_u32_e32 v3, 0, v0
	v_mul_lo_u32 v3, v3, v2
	v_mul_hi_u32 v3, v2, v3
	v_add_u32_e32 v2, v2, v3
	v_mul_hi_u32 v2, v1, v2
	v_mul_lo_u32 v3, v2, v0
	v_sub_u32_e32 v1, v1, v3
	v_add_u32_e32 v5, 1, v2
	v_cmp_ge_u32_e32 vcc, v1, v0
	v_sub_u32_e32 v3, v1, v0
	s_nop 0
	v_cndmask_b32_e32 v2, v2, v5, vcc
	v_cndmask_b32_e32 v1, v1, v3, vcc
	v_add_u32_e32 v3, 1, v2
	v_cmp_ge_u32_e32 vcc, v1, v0
	s_nop 1
	v_cndmask_b32_e32 v2, v2, v3, vcc
	v_mul_lo_u32 v1, v0, v2
	v_add_u32_e32 v0, v1, v0
	v_cmp_ne_u32_e32 vcc, v4, v0
	v_mov_b32_e32 v4, v0
	v_mov_b64_e32 v[0:1], s[10:11]
	s_and_saveexec_b64 s[8:9], vcc
	s_cbranch_execz .LBB0_1954
	v_mov_b32_e32 v0, 0
	global_load_dword v1, v0, s[10:11] offset:-256 sc1
	s_mov_b64 s[20:21], 0
	s_waitcnt vmcnt(0)
	v_cmp_lt_u32_e32 vcc, v1, v4
	s_and_saveexec_b64 s[18:19], vcc
	s_cbranch_execz .LBB0_1953
	s_add_u32 s14, s70, 0x4200
	s_addc_u32 s15, s71, 0
	s_mov_b32 s30, 1
	s_branch .LBB0_1946

.LBB0_1948:
	global_load_dword v1, v0, s[10:11] offset:-256 sc1
	s_add_i32 s30, s30, 1
	s_mov_b64 s[24:25], -1
	s_waitcnt vmcnt(0)
	v_cmp_ge_u32_e32 vcc, v1, v4
	s_orn2_b64 s[28:29], vcc, exec
	s_branch .LBB0_1945

.LBB0_2106:
	s_or_b64 exec, exec, s[10:11]
	v_cvt_f32_u32_e32 v3, v0
	s_waitcnt vmcnt(0)
	v_readfirstlane_b32 s8, v2
	s_add_u32 s10, s70, 0x7500
	s_addc_u32 s11, s71, 0
	v_rcp_iflag_f32_e32 v3, v3
	v_add_u32_e32 v1, s8, v1
	v_add_u32_e32 v4, 1, v1
	s_mov_b64 s[18:19], -1
	v_mul_f32_e32 v2, 0x4f7ffffe, v3
	v_cvt_u32_f32_e32 v2, v2
	v_sub_u32_e32 v3, 0, v0
	v_mul_lo_u32 v3, v3, v2
	v_mul_hi_u32 v3, v2, v3
	v_add_u32_e32 v2, v2, v3
	v_mul_hi_u32 v2, v1, v2
	v_mul_lo_u32 v3, v2, v0
	v_sub_u32_e32 v1, v1, v3
	v_add_u32_e32 v5, 1, v2
	v_cmp_ge_u32_e32 vcc, v1, v0
	v_sub_u32_e32 v3, v1, v0
	s_nop 0
	v_cndmask_b32_e32 v2, v2, v5, vcc
	v_cndmask_b32_e32 v1, v1, v3, vcc
	v_add_u32_e32 v3, 1, v2
	v_cmp_ge_u32_e32 vcc, v1, v0
	s_nop 1
	v_cndmask_b32_e32 v2, v2, v3, vcc
	v_mul_lo_u32 v1, v0, v2
	v_add_u32_e32 v0, v1, v0
	v_cmp_ne_u32_e32 vcc, v4, v0
	v_mov_b32_e32 v4, v0
	v_mov_b64_e32 v[0:1], s[10:11]
	s_and_saveexec_b64 s[8:9], vcc
	s_cbranch_execz .LBB0_2118
	v_mov_b32_e32 v0, 0
	global_load_dword v1, v0, s[10:11] offset:-256 sc1
	s_mov_b64 s[22:23], 0
	s_waitcnt vmcnt(0)
	v_cmp_lt_u32_e32 vcc, v1, v4
	s_and_saveexec_b64 s[20:21], vcc
	s_cbranch_execz .LBB0_2117
	s_add_u32 s18, s70, 0x4200
	s_addc_u32 s19, s71, 0
	s_mov_b32 s34, 1
	s_branch .LBB0_2110

.LBB0_2112:
	global_load_dword v1, v0, s[10:11] offset:-256 sc1
	s_add_i32 s34, s34, 1
	s_mov_b64 s[26:27], -1
	s_waitcnt vmcnt(0)
	v_cmp_ge_u32_e32 vcc, v1, v4
	s_orn2_b64 s[30:31], vcc, exec
	s_branch .LBB0_2109

.LBB0_2264:
	s_or_b64 exec, exec, s[10:11]
	v_cvt_f32_u32_e32 v3, v0
	s_waitcnt vmcnt(0)
	v_readfirstlane_b32 s1, v2
	s_add_u32 s10, s70, 0x7500
	s_addc_u32 s11, s71, 0
	v_rcp_iflag_f32_e32 v3, v3
	v_add_u32_e32 v1, s1, v1
	v_add_u32_e32 v4, 1, v1
	s_mov_b64 s[12:13], -1
	v_mul_f32_e32 v2, 0x4f7ffffe, v3
	v_cvt_u32_f32_e32 v2, v2
	v_sub_u32_e32 v3, 0, v0
	v_mul_lo_u32 v3, v3, v2
	v_mul_hi_u32 v3, v2, v3
	v_add_u32_e32 v2, v2, v3
	v_mul_hi_u32 v2, v1, v2
	v_mul_lo_u32 v3, v2, v0
	v_sub_u32_e32 v1, v1, v3
	v_add_u32_e32 v5, 1, v2
	v_cmp_ge_u32_e32 vcc, v1, v0
	v_sub_u32_e32 v3, v1, v0
	s_nop 0
	v_cndmask_b32_e32 v2, v2, v5, vcc
	v_cndmask_b32_e32 v1, v1, v3, vcc
	v_add_u32_e32 v3, 1, v2
	v_cmp_ge_u32_e32 vcc, v1, v0
	s_nop 1
	v_cndmask_b32_e32 v2, v2, v3, vcc
	v_mul_lo_u32 v1, v0, v2
	v_add_u32_e32 v0, v1, v0
	v_cmp_ne_u32_e32 vcc, v4, v0
	v_mov_b32_e32 v4, v0
	v_mov_b64_e32 v[0:1], s[10:11]
	s_and_saveexec_b64 s[6:7], vcc
	s_cbranch_execz .LBB0_2276
	v_mov_b32_e32 v0, 0
	global_load_dword v1, v0, s[10:11] offset:-256 sc1
	s_mov_b64 s[18:19], 0
	s_waitcnt vmcnt(0)
	v_cmp_lt_u32_e32 vcc, v1, v4
	s_and_saveexec_b64 s[16:17], vcc
	s_cbranch_execz .LBB0_2275
	s_add_u32 s12, s70, 0x4200
	s_addc_u32 s13, s71, 0
	s_mov_b32 s1, 1
	s_branch .LBB0_2268

.LBB0_2270:
	global_load_dword v1, v0, s[10:11] offset:-256 sc1
	s_add_i32 s1, s1, 1
	s_mov_b64 s[22:23], -1
	s_waitcnt vmcnt(0)
	v_cmp_ge_u32_e32 vcc, v1, v4
	s_orn2_b64 s[26:27], vcc, exec
	s_branch .LBB0_2267
